# x15 + layer-1 weight conversion moved out of the prologue into the tail of the layer-0 attention phase: each wave converts one static item then claims chunks of 4 items from a work counter before the
# speedup vs baseline: 1.0291x; 1.0291x over previous
.Lst_claim:
	s_cmp_eq_u32 s88, 0
	s_cbranch_scc1 .Lst_newchunk
	s_add_i32 s88, s88, -1
	s_add_i32 s30, s30, 1
	s_add_i32 s28, s28, 32
	s_branch .Lst_next
.Lst_newchunk:
	s_waitcnt vmcnt(4)
	v_readfirstlane_b32 s30, v140
	s_lshl_b32 s30, s30, 2
	s_add_i32 s30, s30, 0x8200
	s_add_i32 s30, s30, s0
	s_lshl_b32 s28, s30, 5
	s_mov_b32 s88, 3
	s_branch .Lst_next

.LBB0_4:
	v_writelane_b32 v254, s2, 44
	v_mov_b32_e32 v194, v238
	v_readlane_b32 s0, v254, 0
	v_readlane_b32 s1, v254, 1
	s_load_dwordx2 s[94:95], s[0:1], 0x60
	s_load_dwordx16 s[56:71], s[0:1], 0x0
	s_load_dwordx8 s[8:15], s[0:1], 0x40
	v_readfirstlane_b32 s2, v194
	s_ashr_i32 s86, s2, 6
	v_and_b32_e32 v240, 63, v194
	s_mov_b32 s91, s5
	s_waitcnt lgkmcnt(0)
	v_writelane_b32 v254, s8, 45
	s_nop 1
	v_writelane_b32 v254, s9, 46
	v_writelane_b32 v254, s10, 47
	v_writelane_b32 v254, s11, 48
	v_writelane_b32 v254, s12, 49
	v_writelane_b32 v254, s13, 50
	v_writelane_b32 v254, s14, 51
	v_writelane_b32 v254, s15, 52
	s_nop 0
	v_readlane_b32 s0, v254, 4
	v_readlane_b32 s1, v254, 5
	s_load_dword s0, s[0:1], 0x0
	s_waitcnt lgkmcnt(0)
	v_writelane_b32 v254, s0, 53
	s_add_u32 s0, s94, 0x10000
	s_addc_u32 s1, s95, 0
	v_writelane_b32 v254, s0, 54
	s_nop 0
	s_nop 0
	v_writelane_b32 v254, s1, 55
	s_cmp_lg_u32 s100, 2
	s_cbranch_scc1 .Lpp_no
	s_mov_b32 s100, 1
	s_mov_b32 s101, 0x103ff
	s_mov_b32 s88, 0
	s_mov_b64 s[0:1], -1
	s_branch .LBB0_465

.LBB0_471:
	s_cmp_lg_u32 s101, 0x103ff
	s_cbranch_scc1 .Lst_noclaim
	s_cmp_lg_u32 s88, 0
	s_cbranch_scc1 .Lst_noclaim
	s_mov_b64 s[84:85], exec
	v_readlane_b32 s6, v254, 42
	v_readlane_b32 s7, v254, 43
	s_mov_b64 exec, 1
	s_nop 1
	v_mov_b32_e32 v140, 1
	s_nop 3
	global_atomic_add v140, v65, v140, s[6:7] offset:3840 sc0
	s_mov_b64 exec, s[84:85]
